# v019 plus: no L1 invalidate in LN exchange (sc1 slots), barrier leader bumps the generation before its own acquire
# speedup vs baseline: 1.0180x; 1.0080x over previous
;     DI void fused(f32x4 (&acc)[2][2][4][2], const Unit& u, int wr, int wc, int fr, int fq, LAS unsigned char* lds, int wid, int lane) const {
;     ...
;             __builtin_amdgcn_fence(__ATOMIC_ACQUIRE, "agent");
;         }
;         asm volatile("s_waitcnt vmcnt(0) lgkmcnt(0)" ::: "memory"); __builtin_amdgcn_s_barrier(); asm volatile("" ::: "memory");
;         if (lane < 32) {
;             const unsigned long long* slot = xbuf + (size_t)(u.pm * BM + row) * 8; float mt[8], m2[8]; float ms = 0.f;
; #pragma unroll
;             for (int t = 0; t < 8; ++t) { const unsigned long long w = __hip_atomic_load(slot + t, __ATOMIC_RELAXED, __HIP_MEMORY_SCOPE_AGENT); mt[t] = __uint_as_float((unsigned)w); m2[t] = __uint_as_float((unsigned)(w >> 32)); ms += mt[t]; }
;             const float mean = ms * 0.125f; float q = 0.f;
; #pragma unroll
;             for (int t = 0; t < 8; ++t) { const float dm = mt[t] - mean; q += m2[t] + 256.0f * dm * dm; }
;             S[row] = (f32x2v){mean, 1.0f / sqrtf(q * (1.0f / 2048.0f) + LN_EPS)};
.LBB0_192:
.LBB0_193:
	s_waitcnt vmcnt(0) lgkmcnt(0)
	s_barrier
	s_and_saveexec_b64 s[16:17], s[0:1]
	s_cbranch_execz .LBB0_195
	v_readlane_b32 s0, v253, 13
	v_lshlrev_b64 v[130:131], 6, v[130:131]
	v_readlane_b32 s1, v253, 14
	s_nop 1
	v_lshl_add_u64 v[130:131], s[0:1], 0, v[130:131]
	global_load_dwordx2 v[134:135], v[130:131], off sc1
	global_load_dwordx2 v[136:137], v[130:131], off offset:8 sc1
	global_load_dwordx2 v[138:139], v[130:131], off offset:16 sc1
	global_load_dwordx2 v[140:141], v[130:131], off offset:24 sc1
	global_load_dwordx2 v[142:143], v[130:131], off offset:32 sc1
	global_load_dwordx2 v[144:145], v[130:131], off offset:40 sc1
	global_load_dwordx2 v[146:147], v[130:131], off offset:48 sc1
	global_load_dwordx2 v[148:149], v[130:131], off offset:56 sc1
	s_mov_b32 s0, 0xf800000
	s_waitcnt vmcnt(7)
	v_add_f32_e32 v96, 0, v134
	s_waitcnt vmcnt(6)
	v_add_f32_e32 v96, v96, v136
	s_waitcnt vmcnt(5)
	v_add_f32_e32 v96, v96, v138
	s_waitcnt vmcnt(4)
	v_add_f32_e32 v96, v96, v140
	s_waitcnt vmcnt(3)
	v_add_f32_e32 v96, v96, v142
	s_waitcnt vmcnt(2)
	v_add_f32_e32 v96, v96, v144
	s_waitcnt vmcnt(1)
	v_add_f32_e32 v96, v96, v146
	s_waitcnt vmcnt(0)
	v_add_f32_e32 v96, v96, v148
	v_fmamk_f32 v131, v96, 0xbe000000, v134
	v_mul_f32_e32 v133, 0x43800000, v131
	v_fmac_f32_e32 v135, v131, v133
	v_fmamk_f32 v133, v96, 0xbe000000, v136
	v_mul_f32_e32 v134, 0x43800000, v133
	v_fmac_f32_e32 v137, v133, v134
	v_fmamk_f32 v133, v96, 0xbe000000, v138
	v_mul_f32_e32 v134, 0x43800000, v133
	v_fmac_f32_e32 v139, v133, v134
	v_fmamk_f32 v133, v96, 0xbe000000, v140
	v_mul_f32_e32 v134, 0x43800000, v133
	v_fmac_f32_e32 v141, v133, v134
	v_fmamk_f32 v133, v96, 0xbe000000, v142
	v_add_f32_e32 v131, 0, v135
	v_mul_f32_e32 v134, 0x43800000, v133
	v_add_f32_e32 v131, v137, v131
	v_fmac_f32_e32 v143, v133, v134
	v_fmamk_f32 v133, v96, 0xbe000000, v144
	v_add_f32_e32 v131, v139, v131
	v_mul_f32_e32 v134, 0x43800000, v133
	v_add_f32_e32 v131, v141, v131
	v_fmac_f32_e32 v145, v133, v134
	v_fmamk_f32 v133, v96, 0xbe000000, v146
	v_mul_f32_e32 v130, 0x3e000000, v96
	v_add_f32_e32 v131, v143, v131
	v_mul_f32_e32 v134, 0x43800000, v133
	v_fmamk_f32 v96, v96, 0xbe000000, v148
	v_add_f32_e32 v131, v145, v131
	v_fmac_f32_e32 v147, v133, v134
	v_mul_f32_e32 v133, 0x43800000, v96
	v_add_f32_e32 v131, v147, v131
	v_fmac_f32_e32 v149, v96, v133
	v_add_f32_e32 v96, v149, v131
	v_mov_b32_e32 v131, 0x3727c5ac
	v_fmamk_f32 v96, v96, 0x3a000000, v131
	v_cmp_gt_f32_e32 vcc, s0, v96
	v_mul_f32_e32 v131, 0x4f800000, v96
	s_nop 0
	v_cndmask_b32_e32 v96, v96, v131, vcc
	v_sqrt_f32_e32 v131, v96
	s_nop 0
	v_add_u32_e32 v133, -1, v131
	v_fma_f32 v134, -v133, v131, v96
	v_cmp_ge_f32_e64 s[0:1], 0, v134
	v_add_u32_e32 v134, 1, v131
	s_nop 0
	v_cndmask_b32_e64 v133, v131, v133, s[0:1]
	v_fma_f32 v131, -v134, v131, v96
	v_cmp_lt_f32_e64 s[0:1], 0, v131
	s_nop 1
	v_cndmask_b32_e64 v131, v133, v134, s[0:1]
	v_mul_f32_e32 v133, 0x37800000, v131
	v_cndmask_b32_e32 v131, v131, v133, vcc
	v_mov_b32_e32 v133, 0x260
	v_cmp_class_f32_e32 vcc, v96, v133
	s_nop 1
	v_cndmask_b32_e32 v96, v131, v96, vcc
	v_div_scale_f32 v131, s[0:1], v96, v96, 1.0
	v_rcp_f32_e32 v133, v131
	s_nop 0
	v_fma_f32 v134, -v131, v133, 1.0
	v_fmac_f32_e32 v133, v134, v133
	v_div_scale_f32 v134, vcc, 1.0, v96, 1.0
	v_mul_f32_e32 v135, v134, v133
	v_fma_f32 v136, -v131, v135, v134
	v_fmac_f32_e32 v135, v136, v133
	v_fma_f32 v131, -v131, v135, v134
	v_div_fmas_f32 v131, v131, v133, v135
	v_div_fixup_f32 v131, v131, v96, 1.0
	v_lshl_add_u32 v96, v132, 3, 0
	ds_write_b64 v96, v[130:131] offset:8192

; DI unsigned xb_add(unsigned* p, unsigned v) { return __hip_atomic_fetch_add(p, v, __ATOMIC_RELAXED, __HIP_MEMORY_SCOPE_AGENT); }
; DI void xcd_barrier(const XcdBarrier& b) {
;     ...
;             __builtin_amdgcn_fence(__ATOMIC_ACQUIRE, "agent");
;             xb_add(&bar[XB_XGEN(b.x)], 1u);
;             asm volatile("s_waitcnt vmcnt(0)" ::: "memory");
.LBB0_614:
	s_or_b64 exec, exec, s[16:17]
	v_readlane_b32 s4, v254, 42
	v_readlane_b32 s5, v254, 43
	s_waitcnt vmcnt(0)
	s_nop 3
	global_atomic_add v97, v189, s[4:5]
	buffer_inv sc1
	s_waitcnt vmcnt(0)

; DI unsigned xb_add(unsigned* p, unsigned v) { return __hip_atomic_fetch_add(p, v, __ATOMIC_RELAXED, __HIP_MEMORY_SCOPE_AGENT); }
; DI void xcd_barrier_local(const XcdBarrier& b) {
;     ...
;             __builtin_amdgcn_fence(__ATOMIC_ACQUIRE, "agent");
;             xb_add(&bar[XB_XGEN(b.x)], 1u);
;             asm volatile("s_waitcnt vmcnt(0)" ::: "memory");
.LBB0_648:
	s_andn2_saveexec_b64 s[4:5], s[16:17]
	s_cbranch_execz .LBB0_650
	v_readlane_b32 s4, v254, 42
	v_readlane_b32 s5, v254, 43
	s_waitcnt vmcnt(0)
	s_nop 3
	global_atomic_add v97, v189, s[4:5]
	buffer_inv sc1
	s_waitcnt vmcnt(0)
